# phase 0 weight conversion rewritten by hand: 64x64 blocks, 16 dwordx4 loads in flight per wave, no LDS transpose, flat item index over all matrices
# speedup vs baseline: 1.0589x; 1.0526x over previous
.LBB0_13:
	s_waitcnt lgkmcnt(0)
	s_ashr_i32 s15, s16, 6
	s_lshl_b32 s4, s30, 3
	s_add_i32 s14, s4, s15
	v_and_b32_e32 v2, 63, v4
	v_and_b32_e32 v1, 15, v2
	v_lshrrev_b32_e32 v3, 4, v2
	s_mov_b32 s31, s14
	s_cmpk_lt_u32 s31, 0x2e80
	s_cbranch_scc0 .Lcw_done
.Lcw_item:
	s_cmpk_ge_u32 s31, 0x1740
	s_cselect_b32 s33, 1, 0
	s_cselect_b32 s4, 0x1740, 0
	s_sub_u32 s34, s31, s4
	s_cmpk_lt_u32 s34, 0x580
	s_cbranch_scc1 .Lcw_m0
	s_cmpk_lt_u32 s34, 0x840
	s_cbranch_scc1 .Lcw_m1
	s_cmpk_lt_u32 s34, 0xc00
	s_cbranch_scc1 .Lcw_m2
	s_cmpk_lt_u32 s34, 0xc80
	s_cbranch_scc1 .Lcw_m3
	s_cmpk_lt_u32 s34, 0xd00
	s_cbranch_scc1 .Lcw_m4
	s_cmpk_lt_u32 s34, 0xd80
	s_cbranch_scc1 .Lcw_m5
	s_cmpk_lt_u32 s34, 0xe00
	s_cbranch_scc1 .Lcw_m6
	s_cmpk_lt_u32 s34, 0xf00
	s_cbranch_scc1 .Lcw_m7
	s_cmpk_lt_u32 s34, 0x1480
	s_cbranch_scc1 .Lcw_m8
	s_branch .Lcw_m9
.Lcw_m0:
	s_movk_i32 s35, 0x18
	s_movk_i32 s36, 0x20
	s_mov_b32 s37, 0xb00000
	s_movk_i32 s38, 0xb00
	s_movk_i32 s39, 0x400
	s_movk_i32 s40, 0x58
	s_mov_b32 s45, 0x2e8c
	s_mov_b32 s41, 1
	s_movk_i32 s42, 0x10
	s_mov_b32 s29, 1
	s_mov_b32 s43, 0x0
	s_movk_i32 s44, 0x0
	s_branch .Lcw_common
.Lcw_m1:
	s_movk_i32 s35, 0x28
	s_movk_i32 s36, 0x28
	s_mov_b32 s37, 0xb00000
	s_movk_i32 s38, 0x400
	s_movk_i32 s39, 0xb00
	s_movk_i32 s40, 0x10
	s_mov_b32 s45, 0x10000
	s_mov_b32 s41, 0
	s_movk_i32 s42, 0x28
	s_mov_b32 s29, 0
	s_mov_b32 s43, 0xb00000
	s_movk_i32 s44, 0x580
	s_branch .Lcw_common
.Lcw_m2:
	s_movk_i32 s35, 0x38
	s_movk_i32 s36, 0x38
	s_mov_b32 s37, 0x1008000
	s_movk_i32 s38, 0x1008
	s_movk_i32 s39, 0x400
	s_movk_i32 s40, 0x3c
	s_mov_b32 s45, 0x4445
	s_mov_b32 s41, 3
	s_movk_i32 s42, 0x30
	s_mov_b32 s29, 1
	s_mov_b32 s43, 0x1080000
	s_movk_i32 s44, 0x840
	s_branch .Lcw_common
.Lcw_m3:
	s_movk_i32 s35, 0x38
	s_movk_i32 s36, 0x38
	s_mov_b32 s37, 0x1008000
	s_movk_i32 s38, 0x1008
	s_movk_i32 s39, 0x400
	s_movk_i32 s40, 0x8
	s_mov_b32 s45, 0x20000
	s_mov_b32 s41, 4
	s_movk_i32 s42, 0x30
	s_mov_b32 s29, 1
	s_mov_b32 s43, 0x1800000
	s_movk_i32 s44, 0xc00
	s_branch .Lcw_common
.Lcw_m4:
	s_movk_i32 s35, 0x90
	s_movk_i32 s36, 0x90
	s_mov_b32 s37, 0x200000
	s_movk_i32 s38, 0x400
	s_movk_i32 s39, 0x200
	s_movk_i32 s40, 0x10
	s_mov_b32 s45, 0x10000
	s_mov_b32 s41, 2
	s_movk_i32 s42, 0x90
	s_mov_b32 s29, 0
	s_mov_b32 s43, 0x1900000
	s_movk_i32 s44, 0xc80
	s_branch .Lcw_common
.Lcw_m5:
	s_movk_i32 s35, 0x98
	s_movk_i32 s36, 0x98
	s_mov_b32 s37, 0x200000
	s_movk_i32 s38, 0x400
	s_movk_i32 s39, 0x200
	s_movk_i32 s40, 0x10
	s_mov_b32 s45, 0x10000
	s_mov_b32 s41, 0
	s_movk_i32 s42, 0x98
	s_mov_b32 s29, 0
	s_mov_b32 s43, 0x1a00000
	s_movk_i32 s44, 0xd00
	s_branch .Lcw_common
.Lcw_m6:
	s_movk_i32 s35, 0xa0
	s_movk_i32 s36, 0xa0
	s_mov_b32 s37, 0x200000
	s_movk_i32 s38, 0x400
	s_movk_i32 s39, 0x200
	s_movk_i32 s40, 0x10
	s_mov_b32 s45, 0x10000
	s_mov_b32 s41, 0
	s_movk_i32 s42, 0xa0
	s_mov_b32 s29, 0
	s_mov_b32 s43, 0x1b00000
	s_movk_i32 s44, 0xd80
	s_branch .Lcw_common
.Lcw_m7:
	s_movk_i32 s35, 0xa8
	s_movk_i32 s36, 0xa8
	s_mov_b32 s37, 0x400000
	s_movk_i32 s38, 0x400
	s_movk_i32 s39, 0x400
	s_movk_i32 s40, 0x10
	s_mov_b32 s45, 0x10000
	s_mov_b32 s41, 0
	s_movk_i32 s42, 0xa8
	s_mov_b32 s29, 0
	s_mov_b32 s43, 0x1c00000
	s_movk_i32 s44, 0xe00
	s_branch .Lcw_common
.Lcw_m8:
	s_movk_i32 s35, 0xb8
	s_movk_i32 s36, 0xc0
	s_mov_b32 s37, 0xb00000
	s_movk_i32 s38, 0xb00
	s_movk_i32 s39, 0x400
	s_movk_i32 s40, 0x58
	s_mov_b32 s45, 0x2e8c
	s_mov_b32 s41, 1
	s_movk_i32 s42, 0xb0
	s_mov_b32 s29, 1
	s_mov_b32 s43, 0x1e00000
	s_movk_i32 s44, 0xf00
	s_branch .Lcw_common
.Lcw_m9:
	s_movk_i32 s35, 0xc8
	s_movk_i32 s36, 0xc8
	s_mov_b32 s37, 0xb00000
	s_movk_i32 s38, 0x400
	s_movk_i32 s39, 0xb00
	s_movk_i32 s40, 0x10
	s_mov_b32 s45, 0x10000
	s_mov_b32 s41, 0
	s_movk_i32 s42, 0xc8
	s_mov_b32 s29, 0
	s_mov_b32 s43, 0x2900000
	s_movk_i32 s44, 0x1480
.Lcw_common:
	s_load_dwordx2 s[46:47], s[10:11], s35
	s_load_dwordx2 s[48:49], s[10:11], s36
	s_load_dwordx2 s[50:51], s[10:11], s42
	s_sub_u32 s34, s34, s44
	s_mul_i32 s4, s34, s45
	s_lshr_b32 s54, s4, 20
	s_mul_i32 s4, s54, s40
	s_sub_u32 s55, s34, s4
	s_mul_i32 s4, s33, s37
	s_lshl_b32 s5, s33, 12
	s_mul_i32 s8, s33, 0x2e80000
	s_add_u32 s8, s8, s43
	s_add_u32 s8, s8, 0xa00000
	s_add_u32 s52, s12, s8
	s_addc_u32 s53, s13, 0
	s_waitcnt lgkmcnt(0)
	s_add_u32 s46, s46, s4
	s_addc_u32 s47, s47, 0
	s_add_u32 s48, s48, s4
	s_addc_u32 s49, s49, 0
	s_add_u32 s50, s50, s5
	s_addc_u32 s51, s51, 0
	s_cmp_eq_u32 s41, 2
	s_cbranch_scc0 .Lcw_nm2
	s_add_u32 s48, s46, 0x800
	s_addc_u32 s49, s47, 0
.Lcw_nm2:
	s_lshl_b32 s4, s55, 6
	v_lshl_add_u32 v5, v1, 2, s4
	s_lshl_b32 s5, s54, 6
	v_lshl_add_u32 v6, v3, 4, s5
	v_mov_b32_e32 v7, v5
	s_cmp_eq_u32 s41, 0
	s_cbranch_scc1 .Lcw_colok
	s_cmp_eq_u32 s41, 4
	s_cbranch_scc1 .Lcw_mode4
	s_cmp_eq_u32 s41, 3
	s_cbranch_scc1 .Lcw_mode3
	v_lshrrev_b32_e32 v7, 3, v5
	v_lshlrev_b32_e32 v7, 2, v7
	s_branch .Lcw_colok
.Lcw_mode4:
	v_add_u32_e32 v7, 0x600, v5
	s_branch .Lcw_colok
.Lcw_mode3:
	s_movk_i32 s4, 0x5ff
	v_cmp_lt_u32_e32 vcc, s4, v5
	v_add_u32_e32 v8, 0x208, v5
	s_nop 1
	v_cndmask_b32_e32 v7, v5, v8, vcc
	s_movk_i32 s4, 0xdff
	v_cmp_lt_u32_e32 vcc, s4, v5
	v_add_u32_e32 v8, 0xfffffa00, v5
	s_nop 1
	v_cndmask_b32_e32 v7, v7, v8, vcc
.Lcw_colok:
	v_mul_lo_u32 v8, v6, s38
	v_add_u32_e32 v8, v8, v7
	v_lshlrev_b32_e32 v8, 2, v8
	v_mov_b32_e32 v9, 0
	v_lshl_add_u64 v[10:11], v[8:9], 0, s[46:47]
	s_cmp_eq_u32 s41, 1
	s_cbranch_scc1 .Lcw_sel2
	s_cmp_eq_u32 s41, 2
	s_cbranch_scc0 .Lcw_nosel2
.Lcw_sel2:
	v_lshl_add_u64 v[12:13], v[8:9], 0, s[48:49]
	v_and_b32_e32 v14, 4, v5
	v_cmp_ne_u32_e32 vcc, 0, v14
	s_nop 1
	v_cndmask_b32_e32 v10, v10, v12, vcc
	v_cndmask_b32_e32 v11, v11, v13, vcc
.Lcw_nosel2:
	s_cmp_eq_u32 s29, 0
	s_cbranch_scc1 .Lcw_nogain
	v_lshlrev_b32_e32 v14, 2, v6
	global_load_dwordx4 v[16:19], v14, s[50:51]
	global_load_dwordx4 v[20:23], v14, s[50:51] offset:16
	global_load_dwordx4 v[24:27], v14, s[50:51] offset:32
	global_load_dwordx4 v[28:31], v14, s[50:51] offset:48
	s_branch .Lcw_gaindone
.Lcw_nogain:
	v_mov_b32_e32 v16, 1.0
	v_mov_b32_e32 v17, 1.0
	v_mov_b32_e32 v18, 1.0
	v_mov_b32_e32 v19, 1.0
	v_mov_b32_e32 v20, 1.0
	v_mov_b32_e32 v21, 1.0
	v_mov_b32_e32 v22, 1.0
	v_mov_b32_e32 v23, 1.0
	v_mov_b32_e32 v24, 1.0
	v_mov_b32_e32 v25, 1.0
	v_mov_b32_e32 v26, 1.0
	v_mov_b32_e32 v27, 1.0
	v_mov_b32_e32 v28, 1.0
	v_mov_b32_e32 v29, 1.0
	v_mov_b32_e32 v30, 1.0
	v_mov_b32_e32 v31, 1.0
.Lcw_gaindone:
	s_mov_b64 s[16:17], exec
	s_cmp_eq_u32 s41, 3
	s_cbranch_scc0 .Lcw_ld
	s_cmpk_ge_u32 s55, 0x38
	s_cbranch_scc0 .Lcw_ld
	v_mov_b32_e32 v32, 0
	v_mov_b32_e32 v33, 0
	v_mov_b32_e32 v34, 0
	v_mov_b32_e32 v35, 0
	v_mov_b32_e32 v36, 0
	v_mov_b32_e32 v37, 0
	v_mov_b32_e32 v38, 0
	v_mov_b32_e32 v39, 0
	v_mov_b32_e32 v40, 0
	v_mov_b32_e32 v41, 0
	v_mov_b32_e32 v42, 0
	v_mov_b32_e32 v43, 0
	v_mov_b32_e32 v44, 0
	v_mov_b32_e32 v45, 0
	v_mov_b32_e32 v46, 0
	v_mov_b32_e32 v47, 0
	v_mov_b32_e32 v48, 0
	v_mov_b32_e32 v49, 0
	v_mov_b32_e32 v50, 0
	v_mov_b32_e32 v51, 0
	v_mov_b32_e32 v52, 0
	v_mov_b32_e32 v53, 0
	v_mov_b32_e32 v54, 0
	v_mov_b32_e32 v55, 0
	v_mov_b32_e32 v56, 0
	v_mov_b32_e32 v57, 0
	v_mov_b32_e32 v58, 0
	v_mov_b32_e32 v59, 0
	v_mov_b32_e32 v60, 0
	v_mov_b32_e32 v61, 0
	v_mov_b32_e32 v62, 0
	v_mov_b32_e32 v63, 0
	v_mov_b32_e32 v64, 0
	v_mov_b32_e32 v65, 0
	v_mov_b32_e32 v66, 0
	v_mov_b32_e32 v67, 0
	v_mov_b32_e32 v68, 0
	v_mov_b32_e32 v69, 0
	v_mov_b32_e32 v70, 0
	v_mov_b32_e32 v71, 0
	v_mov_b32_e32 v72, 0
	v_mov_b32_e32 v73, 0
	v_mov_b32_e32 v74, 0
	v_mov_b32_e32 v75, 0
	v_mov_b32_e32 v76, 0
	v_mov_b32_e32 v77, 0
	v_mov_b32_e32 v78, 0
	v_mov_b32_e32 v79, 0
	v_mov_b32_e32 v80, 0
	v_mov_b32_e32 v81, 0
	v_mov_b32_e32 v82, 0
	v_mov_b32_e32 v83, 0
	v_mov_b32_e32 v84, 0
	v_mov_b32_e32 v85, 0
	v_mov_b32_e32 v86, 0
	v_mov_b32_e32 v87, 0
	v_mov_b32_e32 v88, 0
	v_mov_b32_e32 v89, 0
	v_mov_b32_e32 v90, 0
	v_mov_b32_e32 v91, 0
	v_mov_b32_e32 v92, 0
	v_mov_b32_e32 v93, 0
	v_mov_b32_e32 v94, 0
	v_mov_b32_e32 v95, 0
	s_movk_i32 s4, 0xe08
	v_cmp_gt_u32_e64 s[6:7], s4, v5
	s_waitcnt vmcnt(0)
	s_nop 3
	s_and_b64 exec, exec, s[6:7]
	s_cbranch_execz .Lcw_lddone
.Lcw_ld:
	s_lshl_b32 s56, s38, 2
	s_mov_b32 s57, 0
	global_load_dwordx4 v[32:35], v[10:11], off
	v_lshl_add_u64 v[10:11], v[10:11], 0, s[56:57]
	global_load_dwordx4 v[36:39], v[10:11], off
	v_lshl_add_u64 v[10:11], v[10:11], 0, s[56:57]
	global_load_dwordx4 v[40:43], v[10:11], off
	v_lshl_add_u64 v[10:11], v[10:11], 0, s[56:57]
	global_load_dwordx4 v[44:47], v[10:11], off
	v_lshl_add_u64 v[10:11], v[10:11], 0, s[56:57]
	global_load_dwordx4 v[48:51], v[10:11], off
	v_lshl_add_u64 v[10:11], v[10:11], 0, s[56:57]
	global_load_dwordx4 v[52:55], v[10:11], off
	v_lshl_add_u64 v[10:11], v[10:11], 0, s[56:57]
	global_load_dwordx4 v[56:59], v[10:11], off
	v_lshl_add_u64 v[10:11], v[10:11], 0, s[56:57]
	global_load_dwordx4 v[60:63], v[10:11], off
	v_lshl_add_u64 v[10:11], v[10:11], 0, s[56:57]
	global_load_dwordx4 v[64:67], v[10:11], off
	v_lshl_add_u64 v[10:11], v[10:11], 0, s[56:57]
	global_load_dwordx4 v[68:71], v[10:11], off
	v_lshl_add_u64 v[10:11], v[10:11], 0, s[56:57]
	global_load_dwordx4 v[72:75], v[10:11], off
	v_lshl_add_u64 v[10:11], v[10:11], 0, s[56:57]
	global_load_dwordx4 v[76:79], v[10:11], off
	v_lshl_add_u64 v[10:11], v[10:11], 0, s[56:57]
	global_load_dwordx4 v[80:83], v[10:11], off
	v_lshl_add_u64 v[10:11], v[10:11], 0, s[56:57]
	global_load_dwordx4 v[84:87], v[10:11], off
	v_lshl_add_u64 v[10:11], v[10:11], 0, s[56:57]
	global_load_dwordx4 v[88:91], v[10:11], off
	v_lshl_add_u64 v[10:11], v[10:11], 0, s[56:57]
	global_load_dwordx4 v[92:95], v[10:11], off
.Lcw_lddone:
	s_mov_b64 exec, s[16:17]
	v_mul_lo_u32 v12, v5, s39
	v_add_u32_e32 v12, v12, v6
	v_lshlrev_b32_e32 v12, 1, v12
	v_mov_b32_e32 v13, 0
	v_lshl_add_u64 v[12:13], v[12:13], 0, s[52:53]
	s_lshl_b32 s8, s39, 1
	s_mov_b32 s9, 0
	s_waitcnt vmcnt(14)
	v_mul_f32_e32 v32, v16, v32
	v_mul_f32_e32 v33, v16, v33
	v_mul_f32_e32 v34, v16, v34
	v_mul_f32_e32 v35, v16, v35
	v_mul_f32_e32 v36, v17, v36
	v_mul_f32_e32 v37, v17, v37
	v_mul_f32_e32 v38, v17, v38
	v_mul_f32_e32 v39, v17, v39
	v_cvt_pk_bf16_f32 v96, v32, v36
	v_cvt_pk_bf16_f32 v104, v33, v37
	v_cvt_pk_bf16_f32 v112, v34, v38
	v_cvt_pk_bf16_f32 v120, v35, v39
	s_waitcnt vmcnt(12)
	v_mul_f32_e32 v40, v18, v40
	v_mul_f32_e32 v41, v18, v41
	v_mul_f32_e32 v42, v18, v42
	v_mul_f32_e32 v43, v18, v43
	v_mul_f32_e32 v44, v19, v44
	v_mul_f32_e32 v45, v19, v45
	v_mul_f32_e32 v46, v19, v46
	v_mul_f32_e32 v47, v19, v47
	v_cvt_pk_bf16_f32 v97, v40, v44
	v_cvt_pk_bf16_f32 v105, v41, v45
	v_cvt_pk_bf16_f32 v113, v42, v46
	v_cvt_pk_bf16_f32 v121, v43, v47
	s_waitcnt vmcnt(10)
	v_mul_f32_e32 v48, v20, v48
	v_mul_f32_e32 v49, v20, v49
	v_mul_f32_e32 v50, v20, v50
	v_mul_f32_e32 v51, v20, v51
	v_mul_f32_e32 v52, v21, v52
	v_mul_f32_e32 v53, v21, v53
	v_mul_f32_e32 v54, v21, v54
	v_mul_f32_e32 v55, v21, v55
	v_cvt_pk_bf16_f32 v98, v48, v52
	v_cvt_pk_bf16_f32 v106, v49, v53
	v_cvt_pk_bf16_f32 v114, v50, v54
	v_cvt_pk_bf16_f32 v122, v51, v55
	s_waitcnt vmcnt(8)
	v_mul_f32_e32 v56, v22, v56
	v_mul_f32_e32 v57, v22, v57
	v_mul_f32_e32 v58, v22, v58
	v_mul_f32_e32 v59, v22, v59
	v_mul_f32_e32 v60, v23, v60
	v_mul_f32_e32 v61, v23, v61
	v_mul_f32_e32 v62, v23, v62
	v_mul_f32_e32 v63, v23, v63
	v_cvt_pk_bf16_f32 v99, v56, v60
	v_cvt_pk_bf16_f32 v107, v57, v61
	v_cvt_pk_bf16_f32 v115, v58, v62
	v_cvt_pk_bf16_f32 v123, v59, v63
	s_waitcnt vmcnt(6)
	v_mul_f32_e32 v64, v24, v64
	v_mul_f32_e32 v65, v24, v65
	v_mul_f32_e32 v66, v24, v66
	v_mul_f32_e32 v67, v24, v67
	v_mul_f32_e32 v68, v25, v68
	v_mul_f32_e32 v69, v25, v69
	v_mul_f32_e32 v70, v25, v70
	v_mul_f32_e32 v71, v25, v71
	v_cvt_pk_bf16_f32 v100, v64, v68
	v_cvt_pk_bf16_f32 v108, v65, v69
	v_cvt_pk_bf16_f32 v116, v66, v70
	v_cvt_pk_bf16_f32 v124, v67, v71
	s_waitcnt vmcnt(4)
	v_mul_f32_e32 v72, v26, v72
	v_mul_f32_e32 v73, v26, v73
	v_mul_f32_e32 v74, v26, v74
	v_mul_f32_e32 v75, v26, v75
	v_mul_f32_e32 v76, v27, v76
	v_mul_f32_e32 v77, v27, v77
	v_mul_f32_e32 v78, v27, v78
	v_mul_f32_e32 v79, v27, v79
	v_cvt_pk_bf16_f32 v101, v72, v76
	v_cvt_pk_bf16_f32 v109, v73, v77
	v_cvt_pk_bf16_f32 v117, v74, v78
	v_cvt_pk_bf16_f32 v125, v75, v79
	s_waitcnt vmcnt(2)
	v_mul_f32_e32 v80, v28, v80
	v_mul_f32_e32 v81, v28, v81
	v_mul_f32_e32 v82, v28, v82
	v_mul_f32_e32 v83, v28, v83
	v_mul_f32_e32 v84, v29, v84
	v_mul_f32_e32 v85, v29, v85
	v_mul_f32_e32 v86, v29, v86
	v_mul_f32_e32 v87, v29, v87
	v_cvt_pk_bf16_f32 v102, v80, v84
	v_cvt_pk_bf16_f32 v110, v81, v85
	v_cvt_pk_bf16_f32 v118, v82, v86
	v_cvt_pk_bf16_f32 v126, v83, v87
	s_waitcnt vmcnt(0)
	v_mul_f32_e32 v88, v30, v88
	v_mul_f32_e32 v89, v30, v89
	v_mul_f32_e32 v90, v30, v90
	v_mul_f32_e32 v91, v30, v91
	v_mul_f32_e32 v92, v31, v92
	v_mul_f32_e32 v93, v31, v93
	v_mul_f32_e32 v94, v31, v94
	v_mul_f32_e32 v95, v31, v95
	v_cvt_pk_bf16_f32 v103, v88, v92
	v_cvt_pk_bf16_f32 v111, v89, v93
	v_cvt_pk_bf16_f32 v119, v90, v94
	v_cvt_pk_bf16_f32 v127, v91, v95
	global_store_dwordx4 v[12:13], v[96:99], off
	global_store_dwordx4 v[12:13], v[100:103], off offset:16
	v_lshl_add_u64 v[12:13], v[12:13], 0, s[8:9]
	global_store_dwordx4 v[12:13], v[104:107], off
	global_store_dwordx4 v[12:13], v[108:111], off offset:16
	v_lshl_add_u64 v[12:13], v[12:13], 0, s[8:9]
	global_store_dwordx4 v[12:13], v[112:115], off
	global_store_dwordx4 v[12:13], v[116:119], off offset:16
	v_lshl_add_u64 v[12:13], v[12:13], 0, s[8:9]
	global_store_dwordx4 v[12:13], v[120:123], off
	global_store_dwordx4 v[12:13], v[124:127], off offset:16
	s_add_u32 s31, s31, s76
	s_cmpk_lt_u32 s31, 0x2e80
	s_cbranch_scc1 .Lcw_item
.Lcw_done:
.LBB0_254:
	s_cmp_gt_i32 s14, 0x800f
	s_cbranch_scc1 .LBB0_273
	v_mbcnt_lo_u32_b32 v1, -1, 0
	v_mbcnt_hi_u32_b32 v3, -1, v1
	v_and_b32_e32 v1, 64, v3
	v_add_u32_e32 v4, 64, v1
	v_xor_b32_e32 v1, 1, v3
	v_cmp_lt_i32_e32 vcc, v1, v4
	v_xor_b32_e32 v5, 2, v3
	s_load_dwordx2 s[16:17], s[10:11], 0xd8
	v_cndmask_b32_e32 v1, v3, v1, vcc
	v_cmp_lt_i32_e32 vcc, v5, v4
	s_add_u32 s20, s12, 0x80000
	v_mov_b32_e32 v19, 0
	v_cndmask_b32_e32 v5, v3, v5, vcc
	v_lshlrev_b32_e32 v30, 2, v5
	v_xor_b32_e32 v5, 4, v3
	v_cmp_lt_i32_e32 vcc, v5, v4
	v_lshlrev_b32_e32 v18, 3, v2
	s_addc_u32 s21, s13, 0
	v_cndmask_b32_e32 v5, v3, v5, vcc
	v_lshlrev_b32_e32 v31, 2, v5
	v_xor_b32_e32 v5, 8, v3
	v_cmp_lt_i32_e32 vcc, v5, v4
	s_lshl_b32 s6, s30, 9
	s_lshl_b32 s7, s15, 6
	v_cndmask_b32_e32 v5, v3, v5, vcc
	v_lshlrev_b32_e32 v32, 2, v5
	v_xor_b32_e32 v5, 16, v3
	v_cmp_lt_i32_e32 vcc, v5, v4
	s_mov_b64 s[4:5], 0x6700000
	s_add_i32 s6, s6, s7
	v_cndmask_b32_e32 v5, v3, v5, vcc
	v_lshlrev_b32_e32 v33, 2, v5
	v_xor_b32_e32 v5, 32, v3
	v_cmp_lt_i32_e32 vcc, v5, v4
	s_ashr_i32 s15, s14, 31
	s_ashr_i32 s77, s76, 31
	v_cndmask_b32_e32 v3, v3, v5, vcc
	v_lshl_add_u64 v[4:5], s[12:13], 0, v[18:19]
	v_lshlrev_b32_e32 v18, 2, v2
	v_lshlrev_b32_e32 v34, 2, v3
	v_lshl_add_u64 v[20:21], v[4:5], 0, s[4:5]
	v_lshl_add_u64 v[4:5], s[12:13], 0, v[18:19]
	s_mov_b64 s[4:5], 0x1ca40000
	v_or_b32_e32 v3, s6, v2
	s_mov_b32 s19, 0
	v_lshlrev_b32_e32 v1, 2, v1
	v_cmp_gt_u32_e64 s[8:9], 4, v2
	v_lshl_add_u64 v[22:23], v[4:5], 0, s[4:5]
	v_cmp_eq_u32_e64 s[4:5], 0, v2
	v_add_u32_e32 v18, 0xffe00000, v3
	s_lshl_b32 s30, s80, 9
	s_lshl_b64 s[22:23], s[14:15], 12
	s_lshl_b64 s[24:25], s[76:77], 12
	s_movk_i32 s31, 0x7fff
	v_lshlrev_b32_e32 v24, 4, v2
	v_mov_b32_e32 v25, v19
	s_mov_b32 s33, 0xffff0000
	s_branch .LBB0_257
